# adds: removal of the dead 64-bit address arithmetic left behind by the glaprep u16-load conversion (192 VALU per unit)
# baseline (speedup 1.0000x reference)
; DI unsigned cvt_pk_bf16(float lo, float hi) { unsigned r; asm("v_cvt_pk_bf16_f32 %0, %1, %2" : "=v"(r) : "v"(lo), "v"(hi)); return r; }
; DI bf16_t f2bf(float f) { unsigned u = __builtin_bit_cast(unsigned, f); return (bf16_t)((u + 0x7fffu + ((u >> 16) & 1u)) >> 16); }
; __device__ void phase_glaprep(const Params& p, unsigned char* shm) {
;     ...
;         for (int ii = 0; ii < 32; ii += 2) {
;             float kh[2];
; #pragma unroll
;             for (int e = 0; e < 2; ++e) { const int i = half * 32 + ii + e; const float E = __expf(g[ii + e] - Gmid), Ei = __builtin_amdgcn_rcpf(E);
;                 const size_t gi = (size_t)(r0 + i) * KD + h * 256 + d;
;                 const float qv = bf2f(Q[gi]) * E, kv = bf2f(Kx[gi]) * Ei; kh[e] = kv * e2d;
;                 Qs[i * 264 + d] = f2bf(qv); Ks[i * 264 + d] = f2bf(kv); Qh[i * 264 + d] = f2bf(qv * e1d); }
;             kt[ii >> 1] = cvt_pk_bf16(kh[0], kh[1]);
;         }
.LBB0_583:
	v_or_b32_e32 v4, s60, v48
	v_lshlrev_b32_e32 v171, 1, v4
	ds_read_u16 v4, v58 offset:8192
	ds_read_u16 v196, v58 offset:41984
	s_nop 0
	ds_read_u16 v194, v61 offset:8192
	s_nop 0
	ds_read_u16 v195, v61 offset:41984
	s_waitcnt lgkmcnt(0)
	v_add_f32_e32 v39, v0, v1
	ds_read_u16 v197, v64 offset:8192
	ds_read_u16 v192, v67 offset:8192
	ds_read_u16 v198, v64 offset:41984
	ds_read_u16 v193, v67 offset:41984
	v_mul_f32_e32 v3, 0x3fb8aa3b, v41
	v_sub_f32_e32 v189, v189, v41
	v_sub_f32_e32 v174, v174, v41
	v_sub_f32_e32 v191, v173, v41
	v_exp_f32_e32 v173, v3
	v_sub_f32_e32 v0, v39, v41
	v_mul_f32_e32 v1, 0x3fb8aa3b, v189
	v_mul_f32_e32 v174, 0x3fb8aa3b, v174
	v_mul_f32_e32 v199, 0x3fb8aa3b, v0
	v_exp_f32_e32 v200, v1
	v_mul_f32_e32 v189, 0x3fb8aa3b, v191
	v_exp_f32_e32 v201, v174
	ds_read_u16 v190, v70 offset:8192
	s_nop 0
	ds_read_u16 v191, v70 offset:41984
	v_rcp_f32_e32 v0, v200
	v_rcp_f32_e32 v1, v201
	v_exp_f32_e32 v174, v199
	v_exp_f32_e32 v189, v189
	v_sub_f32_e32 v182, v182, v41
	v_mul_f32_e32 v182, 0x3fb8aa3b, v182
	v_exp_f32_e32 v182, v182
	v_sub_f32_e32 v181, v181, v41
	v_mul_f32_e32 v181, 0x3fb8aa3b, v181
	v_exp_f32_e32 v181, v181
	v_sub_f32_e32 v180, v180, v41
	v_mul_f32_e32 v180, 0x3fb8aa3b, v180
	v_exp_f32_e32 v180, v180
	v_sub_f32_e32 v5, v5, v41
	v_mul_f32_e32 v5, 0x3fb8aa3b, v5
	v_sub_f32_e32 v179, v179, v41
	v_mul_f32_e32 v179, 0x3fb8aa3b, v179
	v_exp_f32_e32 v179, v179
	v_sub_f32_e32 v6, v6, v41
	v_mul_f32_e32 v6, 0x3fb8aa3b, v6
	v_sub_f32_e32 v178, v178, v41
	v_mul_f32_e32 v178, 0x3fb8aa3b, v178
	v_exp_f32_e32 v178, v178
	v_sub_f32_e32 v7, v7, v41
	v_mul_f32_e32 v7, 0x3fb8aa3b, v7
	v_sub_f32_e32 v177, v177, v41
	v_mul_f32_e32 v177, 0x3fb8aa3b, v177
	v_exp_f32_e32 v177, v177
	v_sub_f32_e32 v8, v8, v41
	v_mul_f32_e32 v8, 0x3fb8aa3b, v8
	v_sub_f32_e32 v176, v176, v41
	v_mul_f32_e32 v176, 0x3fb8aa3b, v176
	v_exp_f32_e32 v176, v176
	v_sub_f32_e32 v9, v9, v41
	v_mul_f32_e32 v9, 0x3fb8aa3b, v9
	v_sub_f32_e32 v175, v175, v41
	s_waitcnt lgkmcnt(9)
	v_lshlrev_b32_e32 v4, 16, v4
	s_waitcnt lgkmcnt(8)
	v_lshlrev_b32_e32 v196, 16, v196
	v_mul_f32_e32 v4, v200, v4
	s_waitcnt lgkmcnt(6)
	v_lshlrev_b32_e32 v195, 16, v195
	v_mul_f32_e32 v0, v0, v196
	v_lshlrev_b32_e32 v194, 16, v194
	v_mul_f32_e32 v1, v1, v195
	v_bfe_u32 v196, v4, 16, 1
	v_bfe_u32 v199, v0, 16, 1
	v_mul_f32_e32 v200, v173, v4
	v_mul_f32_e32 v194, v201, v194
	v_mul_f32_e32 v195, v174, v0
	v_bfe_u32 v203, v1, 16, 1
	v_add3_u32 v4, v4, v196, s78
	v_add3_u32 v0, v0, v199, s78
	v_bfe_u32 v196, v200, 16, 1
	v_mul_f32_e32 v201, v174, v1
	v_bfe_u32 v202, v194, 16, 1
	v_add3_u32 v1, v1, v203, s78
	ds_write_b16_d16_hi v58, v4 offset:8192
	ds_write_b16_d16_hi v58, v0 offset:41984
	v_add3_u32 v0, v200, v196, s78
	v_mul_f32_e32 v204, v173, v194
	v_add3_u32 v194, v194, v202, s78
	ds_write_b16_d16_hi v59, v0
	ds_write_b16_d16_hi v61, v194 offset:8192
	ds_write_b16_d16_hi v61, v1 offset:41984
	ds_read_u16 v194, v73 offset:8192
	ds_read_u16 v196, v73 offset:41984
	v_rcp_f32_e32 v1, v189
	s_waitcnt lgkmcnt(12)
	v_lshlrev_b32_e32 v2, 16, v197
	v_mul_f32_e32 v2, v189, v2
	s_waitcnt lgkmcnt(10)
	v_lshlrev_b32_e32 v3, 16, v198
	v_bfe_u32 v199, v204, 16, 1
	v_mul_f32_e32 v1, v1, v3
	v_bfe_u32 v3, v2, 16, 1
	v_add3_u32 v4, v204, v199, s78
	v_add3_u32 v3, v2, v3, s78
	ds_write_b16_d16_hi v62, v4
	ds_write_b16_d16_hi v64, v3 offset:8192
	v_bfe_u32 v3, v1, 16, 1
	v_mul_f32_e32 v4, v174, v1
	v_add3_u32 v1, v1, v3, s78
	ds_write_b16_d16_hi v64, v1 offset:41984
	v_mul_f32_e32 v1, v173, v2
	v_sub_f32_e32 v2, v188, v41
	v_mul_f32_e32 v2, 0x3fb8aa3b, v2
	v_exp_f32_e32 v2, v2
	v_bfe_u32 v3, v1, 16, 1
	v_add3_u32 v1, v1, v3, s78
	ds_write_b16_d16_hi v65, v1
	v_rcp_f32_e32 v1, v2
	v_lshlrev_b32_e32 v3, 16, v192
	v_mul_f32_e32 v192, v2, v3
	s_waitcnt lgkmcnt(13)
	v_lshlrev_b32_e32 v2, 16, v193
	v_mul_f32_e32 v1, v1, v2
	ds_read_u16 v197, v76 offset:8192
	v_cvt_pk_bf16_f32 v0, v195, v201
	v_bfe_u32 v195, v192, 16, 1
	ds_read_u16 v198, v76 offset:41984
	v_add3_u32 v2, v192, v195, s78
	ds_write_b16_d16_hi v67, v2 offset:8192
	v_bfe_u32 v2, v1, 16, 1
	v_mul_f32_e32 v193, v174, v1
	v_add3_u32 v1, v1, v2, s78
	ds_write_b16_d16_hi v67, v1 offset:41984
	v_mul_f32_e32 v1, v173, v192
	v_bfe_u32 v2, v1, 16, 1
	v_add3_u32 v1, v1, v2, s78
	v_sub_f32_e32 v2, v187, v41
	v_mul_f32_e32 v2, 0x3fb8aa3b, v2
	v_exp_f32_e32 v187, v2
	ds_read_u16 v188, v79 offset:8192
	ds_read_u16 v189, v79 offset:41984
	v_rcp_f32_e32 v2, v187
	s_waitcnt lgkmcnt(15)
	v_lshlrev_b32_e32 v3, 16, v190
	v_mul_f32_e32 v3, v187, v3
	ds_write_b16_d16_hi v68, v1
	v_cvt_pk_bf16_f32 v1, v4, v193
	s_waitcnt lgkmcnt(15)
	v_lshlrev_b32_e32 v4, 16, v191
	v_bfe_u32 v187, v3, 16, 1
	v_mul_f32_e32 v2, v2, v4
	v_add3_u32 v187, v3, v187, s78
	ds_write_b16_d16_hi v70, v187 offset:8192
	v_bfe_u32 v187, v2, 16, 1
	v_mul_f32_e32 v4, v174, v2
	v_add3_u32 v2, v2, v187, s78
	ds_write_b16_d16_hi v70, v2 offset:41984
	v_mul_f32_e32 v2, v173, v3
	v_sub_f32_e32 v3, v186, v41
	v_mul_f32_e32 v3, 0x3fb8aa3b, v3
	v_exp_f32_e32 v3, v3
	v_bfe_u32 v186, v2, 16, 1
	v_add3_u32 v2, v2, v186, s78
	ds_write_b16_d16_hi v71, v2
	v_rcp_f32_e32 v2, v3
	s_waitcnt lgkmcnt(15)
	v_lshlrev_b32_e32 v186, 16, v194
	v_mul_f32_e32 v190, v3, v186
	s_waitcnt lgkmcnt(14)
	v_lshlrev_b32_e32 v3, 16, v196
	v_mul_f32_e32 v191, v2, v3
	v_bfe_u32 v193, v190, 16, 1
	ds_read_u16 v194, v82 offset:8192
	ds_read_u16 v195, v82 offset:41984
	v_add3_u32 v2, v190, v193, s78
	ds_write_b16_d16_hi v73, v2 offset:8192
	v_bfe_u32 v2, v191, 16, 1
	v_add3_u32 v2, v191, v2, s78
	ds_write_b16_d16_hi v73, v2 offset:41984
	v_mul_f32_e32 v2, v173, v190
	v_bfe_u32 v3, v2, 16, 1
	v_add3_u32 v190, v2, v3, s78
	v_sub_f32_e32 v2, v185, v41
	v_mul_f32_e32 v2, 0x3fb8aa3b, v2
	v_exp_f32_e32 v185, v2
	v_mul_f32_e32 v192, v174, v191
	ds_read_u16 v191, v85 offset:8192
	ds_read_u16 v193, v85 offset:41984
	v_rcp_f32_e32 v3, v185
	v_cvt_pk_bf16_f32 v2, v4, v192
	s_waitcnt lgkmcnt(15)
; DI unsigned cvt_pk_bf16(float lo, float hi) { unsigned r; asm("v_cvt_pk_bf16_f32 %0, %1, %2" : "=v"(r) : "v"(lo), "v"(hi)); return r; }
; DI bf16_t f2bf(float f) { unsigned u = __builtin_bit_cast(unsigned, f); return (bf16_t)((u + 0x7fffu + ((u >> 16) & 1u)) >> 16); }
; __device__ void phase_glaprep(const Params& p, unsigned char* shm) {
;     ...
;         for (int ii = 0; ii < 32; ii += 2) {
;             float kh[2];
; #pragma unroll
;             for (int e = 0; e < 2; ++e) { const int i = half * 32 + ii + e; const float E = __expf(g[ii + e] - Gmid), Ei = __builtin_amdgcn_rcpf(E);
;                 const size_t gi = (size_t)(r0 + i) * KD + h * 256 + d;
;                 const float qv = bf2f(Q[gi]) * E, kv = bf2f(Kx[gi]) * Ei; kh[e] = kv * e2d;
;                 Qs[i * 264 + d] = f2bf(qv); Ks[i * 264 + d] = f2bf(kv); Qh[i * 264 + d] = f2bf(qv * e1d); }
;             kt[ii >> 1] = cvt_pk_bf16(kh[0], kh[1]);
;         }
	v_lshlrev_b32_e32 v4, 16, v197
	v_mul_f32_e32 v4, v185, v4
	s_waitcnt lgkmcnt(14)
	v_lshlrev_b32_e32 v185, 16, v198
	v_mul_f32_e32 v3, v3, v185
	v_bfe_u32 v185, v4, 16, 1
	v_add3_u32 v185, v4, v185, s78
	ds_write_b16_d16_hi v74, v190
	ds_write_b16_d16_hi v76, v185 offset:8192
	v_bfe_u32 v185, v3, 16, 1
	v_mul_f32_e32 v190, v174, v3
	v_add3_u32 v3, v3, v185, s78
	ds_write_b16_d16_hi v76, v3 offset:41984
	v_mul_f32_e32 v3, v173, v4
	v_sub_f32_e32 v4, v184, v41
	v_mul_f32_e32 v4, 0x3fb8aa3b, v4
	v_exp_f32_e32 v4, v4
	v_bfe_u32 v184, v3, 16, 1
	v_add3_u32 v3, v3, v184, s78
	ds_write_b16_d16_hi v77, v3
	v_rcp_f32_e32 v3, v4
	s_waitcnt lgkmcnt(15)
	v_lshlrev_b32_e32 v184, 16, v188
	v_mul_f32_e32 v4, v4, v184
	s_waitcnt lgkmcnt(14)
	v_lshlrev_b32_e32 v184, 16, v189
	v_mul_f32_e32 v3, v3, v184
	ds_read_u16 v192, v88 offset:8192
	ds_read_u16 v196, v88 offset:41984
	v_bfe_u32 v189, v4, 16, 1
	v_add3_u32 v184, v4, v189, s78
	ds_write_b16_d16_hi v79, v184 offset:8192
	v_bfe_u32 v184, v3, 16, 1
	v_mul_f32_e32 v188, v174, v3
	v_add3_u32 v3, v3, v184, s78
	ds_read_u16 v186, v91 offset:8192
	ds_read_u16 v187, v91 offset:41984
	ds_write_b16_d16_hi v79, v3 offset:41984
	v_mul_f32_e32 v3, v173, v4
	v_bfe_u32 v4, v3, 16, 1
	v_add3_u32 v3, v3, v4, s78
	v_sub_f32_e32 v4, v183, v41
	v_mul_f32_e32 v4, 0x3fb8aa3b, v4
	v_exp_f32_e32 v4, v4
	ds_write_b16_d16_hi v80, v3
	v_cvt_pk_bf16_f32 v3, v190, v188
	v_mul_f32_e32 v175, 0x3fb8aa3b, v175
	v_rcp_f32_e32 v183, v4
	s_waitcnt lgkmcnt(15)
	v_lshlrev_b32_e32 v184, 16, v194
	v_mul_f32_e32 v4, v4, v184
	s_waitcnt lgkmcnt(15)
	v_lshlrev_b32_e32 v184, 16, v195
	v_mul_f32_e32 v183, v183, v184
	v_bfe_u32 v184, v4, 16, 1
	v_add3_u32 v184, v4, v184, s78
	ds_write_b16_d16_hi v82, v184 offset:8192
	v_bfe_u32 v184, v183, 16, 1
	v_mul_f32_e32 v188, v174, v183
	v_add3_u32 v183, v183, v184, s78
	v_mul_f32_e32 v4, v173, v4
	ds_write_b16_d16_hi v82, v183 offset:41984
	v_bfe_u32 v183, v4, 16, 1
	v_add3_u32 v4, v4, v183, s78
	ds_write_b16_d16_hi v83, v4
	v_rcp_f32_e32 v4, v182
	v_exp_f32_e32 v175, v175
	v_sub_f32_e32 v10, v10, v41
	v_mul_f32_e32 v10, 0x3fb8aa3b, v10
	s_waitcnt lgkmcnt(15)
	v_lshlrev_b32_e32 v183, 16, v191
	v_mul_f32_e32 v189, v182, v183
	s_waitcnt lgkmcnt(14)
	v_lshlrev_b32_e32 v182, 16, v193
	v_mul_f32_e32 v4, v4, v182
	v_bfe_u32 v191, v189, 16, 1
	ds_read_u16 v193, v94 offset:8192
	ds_read_u16 v194, v94 offset:41984
	v_add3_u32 v182, v189, v191, s78
	ds_write_b16_d16_hi v85, v182 offset:8192
	v_bfe_u32 v182, v4, 16, 1
	v_mul_f32_e32 v190, v174, v4
	v_add3_u32 v4, v4, v182, s78
	ds_write_b16_d16_hi v85, v4 offset:41984
	v_mul_f32_e32 v4, v173, v189
	v_bfe_u32 v182, v4, 16, 1
	v_add3_u32 v4, v4, v182, s78
	ds_read_u16 v184, v97 offset:8192
	ds_write_b16_d16_hi v86, v4
	ds_read_u16 v185, v97 offset:41984
	v_rcp_f32_e32 v182, v181
	v_cvt_pk_bf16_f32 v4, v188, v190
	s_waitcnt lgkmcnt(15)
	v_lshlrev_b32_e32 v183, 16, v192
	v_mul_f32_e32 v181, v181, v183
	s_waitcnt lgkmcnt(15)
	v_lshlrev_b32_e32 v183, 16, v196
	v_mul_f32_e32 v182, v182, v183
	v_bfe_u32 v183, v181, 16, 1
	v_add3_u32 v183, v181, v183, s78
	ds_write_b16_d16_hi v88, v183 offset:8192
	v_bfe_u32 v183, v182, 16, 1
	v_mul_f32_e32 v188, v174, v182
	v_add3_u32 v182, v182, v183, s78
	v_mul_f32_e32 v181, v173, v181
	ds_write_b16_d16_hi v88, v182 offset:41984
	v_bfe_u32 v182, v181, 16, 1
	v_add3_u32 v181, v181, v182, s78
	ds_write_b16_d16_hi v89, v181
	v_rcp_f32_e32 v181, v180
	s_waitcnt lgkmcnt(15)
	v_lshlrev_b32_e32 v182, 16, v186
	v_mul_f32_e32 v186, v180, v182
	s_waitcnt lgkmcnt(15)
	v_lshlrev_b32_e32 v180, 16, v187
	v_mul_f32_e32 v187, v181, v180
	v_bfe_u32 v190, v186, 16, 1
	ds_read_u16 v191, v100 offset:8192
	ds_read_u16 v192, v100 offset:41984
	v_add3_u32 v180, v186, v190, s78
	ds_write_b16_d16_hi v91, v180 offset:8192
	v_bfe_u32 v180, v187, 16, 1
	v_add3_u32 v180, v187, v180, s78
	ds_write_b16_d16_hi v91, v180 offset:41984
	v_mul_f32_e32 v180, v173, v186
	v_bfe_u32 v181, v180, 16, 1
	v_add3_u32 v186, v180, v181, s78
	ds_read_u16 v190, v103 offset:8192
	ds_read_u16 v195, v103 offset:41984
	v_mul_f32_e32 v189, v174, v187
	v_exp_f32_e32 v187, v5
	ds_write_b16_d16_hi v92, v186
	v_cvt_pk_bf16_f32 v5, v188, v189
	v_sub_f32_e32 v172, v172, v41
	v_rcp_f32_e32 v180, v187
	v_mul_f32_e32 v172, 0x3fb8aa3b, v172
	v_exp_f32_e32 v172, v172
	v_sub_f32_e32 v11, v11, v41
	v_mul_f32_e32 v11, 0x3fb8aa3b, v11
	v_sub_f32_e32 v170, v170, v41
	v_mul_f32_e32 v170, 0x3fb8aa3b, v170
	v_exp_f32_e32 v170, v170
	s_waitcnt lgkmcnt(15)
	v_lshlrev_b32_e32 v181, 16, v193
	v_mul_f32_e32 v181, v187, v181
	s_waitcnt lgkmcnt(15)
	v_lshlrev_b32_e32 v182, 16, v194
	v_mul_f32_e32 v180, v180, v182
	v_bfe_u32 v182, v181, 16, 1
	v_add3_u32 v182, v181, v182, s78
	ds_write_b16_d16_hi v94, v182 offset:8192
	v_bfe_u32 v182, v180, 16, 1
	v_mul_f32_e32 v186, v174, v180
	v_add3_u32 v180, v180, v182, s78
	ds_write_b16_d16_hi v94, v180 offset:41984
	v_mul_f32_e32 v180, v173, v181
	v_bfe_u32 v181, v180, 16, 1
	v_add3_u32 v180, v180, v181, s78
	ds_write_b16_d16_hi v95, v180
	v_rcp_f32_e32 v180, v179
	v_sub_f32_e32 v169, v169, v41
	s_waitcnt lgkmcnt(15)
	v_lshlrev_b32_e32 v181, 16, v184
	v_mul_f32_e32 v179, v179, v181
	s_waitcnt lgkmcnt(13)
	v_lshlrev_b32_e32 v181, 16, v185
	v_mul_f32_e32 v184, v180, v181
	v_bfe_u32 v187, v179, 16, 1
	ds_read_u16 v188, v106 offset:8192
	ds_read_u16 v189, v106 offset:41984
	v_add3_u32 v180, v179, v187, s78
	ds_write_b16_d16_hi v97, v180 offset:8192
	v_bfe_u32 v180, v184, 16, 1
	v_add3_u32 v180, v184, v180, s78
	v_mul_f32_e32 v179, v173, v179
	v_mul_f32_e32 v185, v174, v184
	ds_write_b16_d16_hi v97, v180 offset:41984
	v_bfe_u32 v180, v179, 16, 1
	v_exp_f32_e32 v184, v6
	v_add3_u32 v179, v179, v180, s78
	ds_write_b16_d16_hi v98, v179
	v_rcp_f32_e32 v179, v184
	ds_read_u16 v182, v109 offset:8192
	v_cvt_pk_bf16_f32 v6, v186, v185
	ds_read_u16 v183, v109 offset:41984
	s_waitcnt lgkmcnt(15)
; DI unsigned cvt_pk_bf16(float lo, float hi) { unsigned r; asm("v_cvt_pk_bf16_f32 %0, %1, %2" : "=v"(r) : "v"(lo), "v"(hi)); return r; }
; DI bf16_t f2bf(float f) { unsigned u = __builtin_bit_cast(unsigned, f); return (bf16_t)((u + 0x7fffu + ((u >> 16) & 1u)) >> 16); }
; __device__ void phase_glaprep(const Params& p, unsigned char* shm) {
;     ...
;         for (int ii = 0; ii < 32; ii += 2) {
;             float kh[2];
; #pragma unroll
;             for (int e = 0; e < 2; ++e) { const int i = half * 32 + ii + e; const float E = __expf(g[ii + e] - Gmid), Ei = __builtin_amdgcn_rcpf(E);
;                 const size_t gi = (size_t)(r0 + i) * KD + h * 256 + d;
;                 const float qv = bf2f(Q[gi]) * E, kv = bf2f(Kx[gi]) * Ei; kh[e] = kv * e2d;
;                 Qs[i * 264 + d] = f2bf(qv); Ks[i * 264 + d] = f2bf(kv); Qh[i * 264 + d] = f2bf(qv * e1d); }
;             kt[ii >> 1] = cvt_pk_bf16(kh[0], kh[1]);
;         }
	v_lshlrev_b32_e32 v180, 16, v191
	v_mul_f32_e32 v180, v184, v180
	s_waitcnt lgkmcnt(15)
	v_lshlrev_b32_e32 v181, 16, v192
	v_mul_f32_e32 v179, v179, v181
	v_bfe_u32 v181, v180, 16, 1
	v_add3_u32 v181, v180, v181, s78
	ds_write_b16_d16_hi v100, v181 offset:8192
	v_bfe_u32 v181, v179, 16, 1
	v_mul_f32_e32 v184, v174, v179
	v_add3_u32 v179, v179, v181, s78
	ds_write_b16_d16_hi v100, v179 offset:41984
	v_mul_f32_e32 v179, v173, v180
	v_bfe_u32 v180, v179, 16, 1
	v_add3_u32 v179, v179, v180, s78
	ds_write_b16_d16_hi v101, v179
	v_rcp_f32_e32 v179, v178
	s_waitcnt lgkmcnt(15)
	v_lshlrev_b32_e32 v180, 16, v190
	v_mul_f32_e32 v185, v178, v180
	s_waitcnt lgkmcnt(14)
	v_lshlrev_b32_e32 v178, 16, v195
	v_mul_f32_e32 v186, v179, v178
	v_bfe_u32 v190, v185, 16, 1
	ds_read_u16 v191, v112 offset:8192
	ds_read_u16 v192, v112 offset:41984
	v_add3_u32 v178, v185, v190, s78
	ds_write_b16_d16_hi v103, v178 offset:8192
	v_bfe_u32 v178, v186, 16, 1
	v_add3_u32 v178, v186, v178, s78
	ds_write_b16_d16_hi v103, v178 offset:41984
	v_mul_f32_e32 v178, v173, v185
	v_bfe_u32 v179, v178, 16, 1
	v_add3_u32 v185, v178, v179, s78
	ds_read_u16 v190, v115 offset:8192
	ds_read_u16 v193, v115 offset:41984
	v_mul_f32_e32 v187, v174, v186
	v_exp_f32_e32 v186, v7
	ds_write_b16_d16_hi v104, v185
	v_cvt_pk_bf16_f32 v7, v184, v187
	v_mul_f32_e32 v169, 0x3fb8aa3b, v169
	v_rcp_f32_e32 v178, v186
	v_exp_f32_e32 v169, v169
	v_sub_f32_e32 v168, v168, v41
	v_mul_f32_e32 v168, 0x3fb8aa3b, v168
	v_sub_f32_e32 v167, v167, v41
	v_mul_f32_e32 v167, 0x3fb8aa3b, v167
	v_exp_f32_e32 v167, v167
	s_waitcnt lgkmcnt(15)
	v_lshlrev_b32_e32 v179, 16, v188
	v_mul_f32_e32 v179, v186, v179
	s_waitcnt lgkmcnt(15)
	v_lshlrev_b32_e32 v180, 16, v189
	v_mul_f32_e32 v178, v178, v180
	v_bfe_u32 v180, v179, 16, 1
	v_add3_u32 v180, v179, v180, s78
	ds_write_b16_d16_hi v106, v180 offset:8192
	v_bfe_u32 v180, v178, 16, 1
	v_mul_f32_e32 v184, v174, v178
	v_add3_u32 v178, v178, v180, s78
	ds_write_b16_d16_hi v106, v178 offset:41984
	v_mul_f32_e32 v178, v173, v179
	v_bfe_u32 v179, v178, 16, 1
	v_add3_u32 v178, v178, v179, s78
	ds_write_b16_d16_hi v107, v178
	v_rcp_f32_e32 v178, v177
	v_sub_f32_e32 v12, v12, v41
	v_mul_f32_e32 v12, 0x3fb8aa3b, v12
	v_exp_f32_e32 v12, v12
	v_sub_f32_e32 v38, v38, v41
	s_waitcnt lgkmcnt(14)
	v_lshlrev_b32_e32 v179, 16, v182
	v_mul_f32_e32 v177, v177, v179
	s_waitcnt lgkmcnt(13)
	v_lshlrev_b32_e32 v179, 16, v183
	v_mul_f32_e32 v182, v178, v179
	v_bfe_u32 v185, v177, 16, 1
	ds_read_u16 v186, v118 offset:8192
	ds_read_u16 v187, v118 offset:41984
	v_add3_u32 v178, v177, v185, s78
	ds_write_b16_d16_hi v109, v178 offset:8192
	v_bfe_u32 v178, v182, 16, 1
	v_add3_u32 v178, v182, v178, s78
	v_mul_f32_e32 v177, v173, v177
	v_mul_f32_e32 v183, v174, v182
	ds_write_b16_d16_hi v109, v178 offset:41984
	v_bfe_u32 v178, v177, 16, 1
	v_exp_f32_e32 v182, v8
	v_add3_u32 v177, v177, v178, s78
	ds_write_b16_d16_hi v110, v177
	v_rcp_f32_e32 v177, v182
	ds_read_u16 v180, v121 offset:8192
	v_cvt_pk_bf16_f32 v8, v184, v183
	ds_read_u16 v181, v121 offset:41984
	s_waitcnt lgkmcnt(15)
	v_lshlrev_b32_e32 v178, 16, v191
	v_mul_f32_e32 v178, v182, v178
	s_waitcnt lgkmcnt(15)
	v_lshlrev_b32_e32 v179, 16, v192
	v_mul_f32_e32 v177, v177, v179
	v_bfe_u32 v179, v178, 16, 1
	v_add3_u32 v179, v178, v179, s78
	ds_write_b16_d16_hi v112, v179 offset:8192
	v_bfe_u32 v179, v177, 16, 1
	v_mul_f32_e32 v182, v174, v177
	v_add3_u32 v177, v177, v179, s78
	ds_write_b16_d16_hi v112, v177 offset:41984
	v_mul_f32_e32 v177, v173, v178
	v_bfe_u32 v178, v177, 16, 1
	v_add3_u32 v177, v177, v178, s78
	ds_write_b16_d16_hi v113, v177
	v_rcp_f32_e32 v177, v176
	s_waitcnt lgkmcnt(15)
	v_lshlrev_b32_e32 v178, 16, v190
	v_mul_f32_e32 v183, v176, v178
	s_waitcnt lgkmcnt(14)
	v_lshlrev_b32_e32 v176, 16, v193
	v_mul_f32_e32 v184, v177, v176
	v_bfe_u32 v188, v183, 16, 1
	ds_read_u16 v189, v124 offset:8192
	ds_read_u16 v190, v124 offset:41984
	v_add3_u32 v176, v183, v188, s78
	ds_write_b16_d16_hi v115, v176 offset:8192
	v_bfe_u32 v176, v184, 16, 1
	v_add3_u32 v176, v184, v176, s78
	ds_write_b16_d16_hi v115, v176 offset:41984
	v_mul_f32_e32 v176, v173, v183
	v_bfe_u32 v177, v176, 16, 1
	v_add3_u32 v183, v176, v177, s78
	ds_read_u16 v188, v127 offset:8192
	ds_read_u16 v191, v127 offset:41984
	v_mul_f32_e32 v185, v174, v184
	v_exp_f32_e32 v184, v9
	ds_write_b16_d16_hi v116, v183
	v_cvt_pk_bf16_f32 v9, v182, v185
	v_mul_f32_e32 v38, 0x3fb8aa3b, v38
	v_rcp_f32_e32 v176, v184
	v_exp_f32_e32 v38, v38
	s_waitcnt lgkmcnt(15)
	v_lshlrev_b32_e32 v177, 16, v186
	v_mul_f32_e32 v177, v184, v177
	s_waitcnt lgkmcnt(15)
	v_lshlrev_b32_e32 v178, 16, v187
	v_mul_f32_e32 v176, v176, v178
	v_bfe_u32 v178, v177, 16, 1
	v_add3_u32 v178, v177, v178, s78
	ds_write_b16_d16_hi v118, v178 offset:8192
	v_bfe_u32 v178, v176, 16, 1
	v_mul_f32_e32 v182, v174, v176
	v_add3_u32 v176, v176, v178, s78
	ds_write_b16_d16_hi v118, v176 offset:41984
	v_mul_f32_e32 v176, v173, v177
	v_bfe_u32 v177, v176, 16, 1
	v_add3_u32 v176, v176, v177, s78
	ds_write_b16_d16_hi v119, v176
	v_rcp_f32_e32 v176, v175
	s_waitcnt lgkmcnt(14)
	v_lshlrev_b32_e32 v177, 16, v180
	v_mul_f32_e32 v175, v175, v177
	s_waitcnt lgkmcnt(13)
	v_lshlrev_b32_e32 v177, 16, v181
	v_mul_f32_e32 v180, v176, v177
	v_bfe_u32 v183, v175, 16, 1
	ds_read_u16 v184, v130 offset:8192
	ds_read_u16 v185, v130 offset:41984
	v_add3_u32 v176, v175, v183, s78
	ds_write_b16_d16_hi v121, v176 offset:8192
	v_bfe_u32 v176, v180, 16, 1
	v_add3_u32 v176, v180, v176, s78
	v_mul_f32_e32 v175, v173, v175
	v_mul_f32_e32 v181, v174, v180
	ds_write_b16_d16_hi v121, v176 offset:41984
	v_bfe_u32 v176, v175, 16, 1
	v_exp_f32_e32 v180, v10
	v_add3_u32 v175, v175, v176, s78
	ds_write_b16_d16_hi v122, v175
	v_rcp_f32_e32 v175, v180
	ds_read_u16 v183, v133 offset:8192
	ds_read_u16 v186, v133 offset:41984
	s_waitcnt lgkmcnt(15)
; DI unsigned cvt_pk_bf16(float lo, float hi) { unsigned r; asm("v_cvt_pk_bf16_f32 %0, %1, %2" : "=v"(r) : "v"(lo), "v"(hi)); return r; }
; DI bf16_t f2bf(float f) { unsigned u = __builtin_bit_cast(unsigned, f); return (bf16_t)((u + 0x7fffu + ((u >> 16) & 1u)) >> 16); }
; __device__ void phase_glaprep(const Params& p, unsigned char* shm) {
;     ...
;         for (int ii = 0; ii < 32; ii += 2) {
;             float kh[2];
; #pragma unroll
;             for (int e = 0; e < 2; ++e) { const int i = half * 32 + ii + e; const float E = __expf(g[ii + e] - Gmid), Ei = __builtin_amdgcn_rcpf(E);
;                 const size_t gi = (size_t)(r0 + i) * KD + h * 256 + d;
;                 const float qv = bf2f(Q[gi]) * E, kv = bf2f(Kx[gi]) * Ei; kh[e] = kv * e2d;
;                 Qs[i * 264 + d] = f2bf(qv); Ks[i * 264 + d] = f2bf(kv); Qh[i * 264 + d] = f2bf(qv * e1d); }
;             kt[ii >> 1] = cvt_pk_bf16(kh[0], kh[1]);
;         }
; #pragma unroll
;         for (int cc = 0; cc < 4; ++cc) { const int c = half * 4 + cc, cs = c ^ ((d >> 1) & 7);
;             u32x4 v; v.x = kt[cc * 4]; v.y = kt[cc * 4 + 1]; v.z = kt[cc * 4 + 2]; v.w = kt[cc * 4 + 3];
;             *(u32x4*)(kimg + (size_t)unit * 32768 + d * 128 + cs * 16) = v; }
	v_lshlrev_b32_e32 v176, 16, v189
	v_mul_f32_e32 v176, v180, v176
	s_waitcnt lgkmcnt(15)
	v_lshlrev_b32_e32 v177, 16, v190
	v_mul_f32_e32 v175, v175, v177
	v_bfe_u32 v177, v176, 16, 1
	v_add3_u32 v177, v176, v177, s78
	ds_write_b16_d16_hi v124, v177 offset:8192
	v_bfe_u32 v177, v175, 16, 1
	v_mul_f32_e32 v180, v174, v175
	v_add3_u32 v175, v175, v177, s78
	ds_write_b16_d16_hi v124, v175 offset:41984
	v_mul_f32_e32 v175, v173, v176
	v_bfe_u32 v176, v175, 16, 1
	v_add3_u32 v175, v175, v176, s78
	ds_write_b16_d16_hi v125, v175
	v_rcp_f32_e32 v175, v172
	s_waitcnt lgkmcnt(15)
	v_lshlrev_b32_e32 v176, 16, v188
	v_mul_f32_e32 v172, v172, v176
	s_waitcnt lgkmcnt(14)
	v_lshlrev_b32_e32 v176, 16, v191
	v_mul_f32_e32 v175, v175, v176
	ds_read_u16 v187, v137 offset:8192
	ds_read_u16 v188, v137 offset:41984
	v_cvt_pk_bf16_f32 v10, v182, v181
	v_bfe_u32 v182, v172, 16, 1
	v_add3_u32 v176, v172, v182, s78
	ds_write_b16_d16_hi v127, v176 offset:8192
	v_bfe_u32 v176, v175, 16, 1
	v_exp_f32_e32 v182, v11
	v_mul_f32_e32 v181, v174, v175
	v_add3_u32 v175, v175, v176, s78
	v_mul_f32_e32 v172, v173, v172
	ds_write_b16_d16_hi v127, v175 offset:41984
	v_bfe_u32 v175, v172, 16, 1
	v_add3_u32 v11, v172, v175, s78
	v_rcp_f32_e32 v172, v182
	ds_write_b16_d16_hi v128, v11
	v_cvt_pk_bf16_f32 v11, v180, v181
	ds_read_u16 v175, v140 offset:8192
	ds_read_u16 v180, v140 offset:41984
	s_waitcnt lgkmcnt(15)
	v_lshlrev_b32_e32 v176, 16, v184
	v_mul_f32_e32 v176, v182, v176
	s_waitcnt lgkmcnt(15)
	v_lshlrev_b32_e32 v177, 16, v185
	v_mul_f32_e32 v172, v172, v177
	v_bfe_u32 v177, v176, 16, 1
	v_add3_u32 v177, v176, v177, s78
	ds_write_b16_d16_hi v130, v177 offset:8192
	v_bfe_u32 v177, v172, 16, 1
	v_mul_f32_e32 v181, v174, v172
	v_add3_u32 v172, v172, v177, s78
	ds_write_b16_d16_hi v130, v172 offset:41984
	v_mul_f32_e32 v172, v173, v176
	v_bfe_u32 v176, v172, 16, 1
	v_add3_u32 v172, v172, v176, s78
	ds_write_b16_d16_hi v131, v172
	v_rcp_f32_e32 v172, v170
	s_waitcnt lgkmcnt(14)
	v_lshlrev_b32_e32 v176, 16, v183
	v_mul_f32_e32 v170, v170, v176
	s_waitcnt lgkmcnt(13)
	v_lshlrev_b32_e32 v176, 16, v186
	v_mul_f32_e32 v172, v172, v176
	v_bfe_u32 v183, v170, 16, 1
	ds_read_u16 v184, v143 offset:8192
	ds_read_u16 v185, v143 offset:41984
	v_add3_u32 v176, v170, v183, s78
	ds_write_b16_d16_hi v133, v176 offset:8192
	v_bfe_u32 v176, v172, 16, 1
	v_mul_f32_e32 v182, v174, v172
	v_add3_u32 v172, v172, v176, s78
	v_mul_f32_e32 v170, v173, v170
	ds_write_b16_d16_hi v133, v172 offset:41984
	v_bfe_u32 v172, v170, 16, 1
	v_add3_u32 v170, v170, v172, s78
	ds_read_u16 v172, v146 offset:8192
	ds_read_u16 v183, v146 offset:41984
	v_rcp_f32_e32 v176, v169
	s_waitcnt lgkmcnt(15)
	v_lshlrev_b32_e32 v177, 16, v187
	v_mul_f32_e32 v169, v169, v177
	s_waitcnt lgkmcnt(14)
	v_lshlrev_b32_e32 v177, 16, v188
	ds_write_b16_d16_hi v134, v170
	v_cvt_pk_bf16_f32 v170, v181, v182
	v_mul_f32_e32 v181, v176, v177
	v_bfe_u32 v176, v169, 16, 1
	v_add3_u32 v176, v169, v176, s78
	ds_write_b16_d16_hi v137, v176 offset:8192
	ds_read_u16 v178, v149 offset:8192
	ds_read_u16 v179, v149 offset:41984
	v_bfe_u32 v186, v181, 16, 1
	v_mul_f32_e32 v169, v173, v169
	v_mul_f32_e32 v182, v174, v181
	v_add3_u32 v176, v181, v186, s78
	v_exp_f32_e32 v181, v168
	v_bfe_u32 v168, v169, 16, 1
	v_add3_u32 v168, v169, v168, s78
	ds_write_b16_d16_hi v138, v168
	ds_write_b16_d16_hi v137, v176 offset:41984
	ds_read_u16 v176, v152 offset:8192
	ds_read_u16 v168, v152 offset:41984
	v_rcp_f32_e32 v186, v181
	s_waitcnt lgkmcnt(15)
	v_lshlrev_b32_e32 v175, 16, v175
	v_mul_f32_e32 v169, v181, v175
	s_waitcnt lgkmcnt(15)
	v_lshlrev_b32_e32 v171, 16, v180
	v_bfe_u32 v177, v169, 16, 1
	v_mul_f32_e32 v171, v186, v171
	v_add3_u32 v177, v169, v177, s78
	ds_write_b16_d16_hi v140, v177 offset:8192
	v_bfe_u32 v177, v171, 16, 1
	v_mul_f32_e32 v175, v174, v171
	v_add3_u32 v171, v171, v177, s78
	v_mul_f32_e32 v169, v173, v169
	ds_write_b16_d16_hi v140, v171 offset:41984
	v_bfe_u32 v171, v169, 16, 1
	v_add3_u32 v169, v169, v171, s78
	ds_write_b16_d16_hi v141, v169
	v_rcp_f32_e32 v169, v167
	v_cvt_pk_bf16_f32 v171, v182, v175
	s_ashr_i32 s57, s56, 31
	s_lshl_b64 s[58:59], s[56:57], 15
	s_waitcnt lgkmcnt(15)
	v_lshlrev_b32_e32 v175, 16, v184
	v_mul_f32_e32 v167, v167, v175
	s_waitcnt lgkmcnt(15)
	v_lshlrev_b32_e32 v175, 16, v185
	v_bfe_u32 v177, v167, 16, 1
	v_mul_f32_e32 v169, v169, v175
	v_add3_u32 v177, v167, v177, s78
	ds_write_b16_d16_hi v143, v177 offset:8192
	v_bfe_u32 v177, v169, 16, 1
	v_mul_f32_e32 v175, v174, v169
	v_add3_u32 v169, v169, v177, s78
	v_mul_f32_e32 v167, v173, v167
	ds_write_b16_d16_hi v143, v169 offset:41984
	v_bfe_u32 v169, v167, 16, 1
	v_add3_u32 v167, v167, v169, s78
	ds_write_b16_d16_hi v144, v167
	v_rcp_f32_e32 v167, v12
	s_waitcnt lgkmcnt(15)
	v_lshlrev_b32_e32 v169, 16, v172
	v_mul_f32_e32 v12, v12, v169
	s_waitcnt lgkmcnt(14)
	v_lshlrev_b32_e32 v169, 16, v183
	v_bfe_u32 v172, v12, 16, 1
	v_mul_f32_e32 v167, v167, v169
	v_add3_u32 v172, v12, v172, s78
	ds_write_b16_d16_hi v146, v172 offset:8192
	v_bfe_u32 v172, v167, 16, 1
	v_mul_f32_e32 v169, v174, v167
	v_add3_u32 v167, v167, v172, s78
	v_mul_f32_e32 v12, v173, v12
	ds_write_b16_d16_hi v146, v167 offset:41984
	v_bfe_u32 v167, v12, 16, 1
	v_add3_u32 v12, v12, v167, s78
	ds_write_b16_d16_hi v147, v12
	v_rcp_f32_e32 v12, v38
	v_cvt_pk_bf16_f32 v172, v175, v169
	s_waitcnt lgkmcnt(14)
	v_lshlrev_b32_e32 v167, 16, v178
	v_mul_f32_e32 v38, v38, v167
	s_waitcnt lgkmcnt(13)
	v_lshlrev_b32_e32 v167, 16, v179
	v_bfe_u32 v169, v38, 16, 1
	v_mul_f32_e32 v12, v12, v167
	v_add3_u32 v169, v38, v169, s78
	ds_write_b16_d16_hi v149, v169 offset:8192
	v_bfe_u32 v169, v12, 16, 1
	v_mul_f32_e32 v167, v174, v12
	v_add3_u32 v12, v12, v169, s78
	ds_write_b16_d16_hi v149, v12 offset:41984
	v_mul_f32_e32 v12, v173, v38
	v_sub_f32_e32 v38, v40, v41
	v_mul_f32_e32 v38, 0x3fb8aa3b, v38
	v_exp_f32_e32 v38, v38
	v_bfe_u32 v40, v12, 16, 1
	v_add3_u32 v12, v12, v40, s78
	ds_write_b16_d16_hi v150, v12
	v_rcp_f32_e32 v12, v38
	s_waitcnt lgkmcnt(13)
	v_lshlrev_b32_e32 v40, 16, v176
	v_mul_f32_e32 v38, v38, v40
	s_waitcnt lgkmcnt(12)
	v_lshlrev_b32_e32 v40, 16, v168
	v_bfe_u32 v41, v38, 16, 1
	v_mul_f32_e32 v12, v12, v40
	v_add3_u32 v41, v38, v41, s78
	ds_write_b16_d16_hi v152, v41 offset:8192
	v_bfe_u32 v41, v12, 16, 1
	v_mul_f32_e32 v40, v174, v12
	v_add3_u32 v12, v12, v41, s78
	ds_write_b16_d16_hi v152, v12 offset:41984
	v_mul_f32_e32 v12, v173, v38
	v_cvt_pk_bf16_f32 v173, v167, v40
	v_lshl_add_u64 v[40:41], v[16:17], 0, s[58:59]
	v_lshl_add_u64 v[168:169], v[40:41], 0, v[20:21]
	global_store_dwordx4 v[168:169], v[0:3], off
	v_bfe_u32 v38, v12, 16, 1
	v_add3_u32 v12, v12, v38, s78
	v_lshl_add_u64 v[0:1], v[40:41], 0, v[22:23]
	global_store_dwordx4 v[0:1], v[4:7], off
	v_lshl_add_u64 v[0:1], v[40:41], 0, v[24:25]
	global_store_dwordx4 v[0:1], v[8:11], off
	v_lshl_add_u64 v[0:1], v[40:41], 0, v[26:27]
	ds_write_b16_d16_hi v153, v12
	global_store_dwordx4 v[0:1], v[170:173], off
	s_and_saveexec_b64 s[60:61], s[4:5]
	s_cbranch_execz .LBB0_585
; __device__ void phase_glaprep(const Params& p, unsigned char* shm) {
;     ...
;         if (half == 0) e12[(size_t)unit * 256 + d] = __expf(Glast);
	v_mul_f32_e32 v0, 0x3fb8aa3b, v39
	v_exp_f32_e32 v2, v0
	s_lshl_b64 s[0:1], s[56:57], 10
	v_lshl_add_u64 v[0:1], v[18:19], 0, s[0:1]
	global_store_dword v[0:1], v2, off
